# UQ GEMM tiles reassigned to WGs 128-255 (stride 128) so WGs 0-127 only carry the K-path UKV tile
# speedup vs baseline: 1.0143x; 1.0048x over previous
; #define PG8_STAGE(bufoff, gbase, voff) do { _Pragma("unroll") for (int _i = 0; _i < 2; ++_i) \
;         __builtin_amdgcn_global_load_lds((const unsigned*)((const char*)(gbase) + (voff)[_i]), (PG8_LAS unsigned*)(lds + (bufoff) + ldsw + _i * 8192), 16, 0, 0); } while (0)
; #define PG8_WAIT_V(n) asm volatile("s_waitcnt vmcnt(" #n ")" ::: "memory")
; #define PG8_BAR __builtin_amdgcn_s_barrier()
;     __host__ __device__ bool next(int i, Unit& u) const {
;         const long L = (long)i * G + c; if (L >= nwg) return false;
;         int wgid = (int)L; { const int q = nwg / NXCD, r = nwg % NXCD, xcd = wgid % NXCD, off = wgid / NXCD; wgid = (xcd < r ? xcd * (q + 1) : r * (q + 1) + (xcd - r) * q) + off; }
;         const int nig = WGM * nN, gid = wgid / nig, fm = gid * WGM, gsz = (nM - fm) < WGM ? (nM - fm) : WGM;
;         u.pm = fm + ((wgid % nig) % gsz); u.pn = (wgid % nig) / gsz; return true;
;     }
; template <class Epi, class Sched, bool ALIGN_EPI>
; __device__ __forceinline__ void gemm_phase(PG8_LAS unsigned char* lds, const Gemm g, const Sched& S, const Epi& E) {
;     ...
;     Unit cur, nxt; int ui = 0;
;     if (!S.next(0, cur)) return;
;     f32x4 acc[2][2][4][2];
; #pragma unroll
;     for (int a = 0; a < 2; ++a)
; #pragma unroll
;         for (int b = 0; b < 2; ++b)
; #pragma unroll
;             for (int m = 0; m < 4; ++m)
; #pragma unroll
;                 for (int n = 0; n < 2; ++n) acc[a][b][m][n] = (f32x4){0.f, 0.f, 0.f, 0.f};
;     bf16x8 At[4][2], B0[2][2], B1[2][2];
;     const char* cA = (const char*)g.A + (size_t)cur.pm * tstepA; const char* cB = (const char*)g.Bt + (size_t)cur.pn * tstepB;
;     PG8_STAGE(PG8_SB(0, 0), cB, voffB); PG8_STAGE(PG8_SB(0, 1), cB + hstepB, voffB); PG8_STAGE(PG8_SA(0, 0), cA, voffA); PG8_STAGE(PG8_SA(0, 1), cA + hstepA, voffA);
;     if (wr == 1) PG8_BAR;
;     PG8_WAIT_V(2); PG8_BAR;
;     PG8_STAGE(PG8_SB(1, 0), cB + kstep, voffB); PG8_STAGE(PG8_SA(1, 0), cA + kstep, voffA); PG8_STAGE(PG8_SB(1, 1), cB + hstepB + kstep, voffB);
;     PG8_WAIT_V(6); PG8_BAR;
.LBB0_100:
	s_ashr_i32 s54, s36, 31
	s_lshr_b32 s2, s54, 29
	s_add_i32 s2, s36, s2
	s_ashr_i32 s10, s2, 3
	s_and_b32 s2, s2, -8
	s_sub_i32 s12, s36, s2
	s_cmp_lt_i32 s12, 0
	v_mov_b32_e32 v18, v244
	v_writelane_b32 v255, s28, 20
	s_cselect_b64 s[18:19], -1, 0
	s_mov_b32 s98, s64
	s_mov_b32 s99, s36
	s_cmp_lg_u32 s64, 0x100
	s_cbranch_scc1 .Luq_map
	s_movk_i32 s98, 0x80
	s_sub_i32 s99, s36, 0x80
.Luq_map:
	s_cmp_lt_u32 s99, 0xc0
	s_movk_i32 s2, 0x100
	v_readfirstlane_b32 s13, v18
	v_writelane_b32 v255, s29, 21
	s_cbranch_scc0 .LBB0_115
	v_lshlrev_b32_e32 v0, 4, v18
	v_add_u32_e32 v2, 0x2000, v0
	s_waitcnt lgkmcnt(0)
	v_ashrrev_i32_e32 v3, 31, v2
	v_lshrrev_b32_e32 v3, 22, v3
	v_add_u32_e32 v3, v2, v3
	v_ashrrev_i32_e32 v10, 10, v3
	v_mul_i32_i24_e32 v3, 0x400, v10
	v_sub_u32_e32 v2, v2, v3
	v_lshrrev_b32_e32 v3, 4, v2
	v_bitop3_b32 v2, v3, v2, 32 bitop3:0x6c
	v_ashrrev_i32_e32 v3, 31, v2
	v_lshrrev_b32_e32 v3, 26, v3
	v_add_u32_e32 v3, v2, v3
	v_lshlrev_b32_e32 v4, 3, v10
	v_ashrrev_i32_e32 v11, 6, v3
	v_and_b32_e32 v4, -16, v4
	v_add_u32_e32 v4, v11, v4
	v_and_b32_e32 v5, 3, v11
	s_mov_b32 s20, 0x7fffe0
	v_lshrrev_b32_e32 v6, 2, v4
	v_lshlrev_b32_e32 v7, 1, v4
	v_and_b32_e32 v3, 0xc0, v3
	v_and_or_b32 v5, v4, s20, v5
	v_and_b32_e32 v6, 4, v6
	v_and_b32_e32 v7, 24, v7
	v_sub_u32_e32 v2, v2, v3
	v_or3_b32 v5, v5, v6, v7
	v_lshlrev_b32_e32 v6, 5, v10
	v_ashrrev_i16_sdwa v2, v242, sext(v2) dst_sel:DWORD dst_unused:UNUSED_PAD src0_sel:DWORD src1_sel:BYTE_0
	v_and_b32_e32 v12, 32, v6
	v_bfe_i32 v13, v2, 0, 16
	v_add_u32_e32 v2, v12, v13
	v_lshlrev_b32_e32 v3, 1, v2
	s_movk_i32 s17, 0x1200
	v_lshl_add_u32 v154, v5, 9, v3
	v_mul_lo_u32 v3, v4, s17
	v_add_lshl_u32 v156, v2, v3, 1
	v_bfe_i32 v2, v18, 27, 1
	v_lshrrev_b32_e32 v2, 22, v2
	v_add_u32_e32 v2, v0, v2
	v_and_b32_e32 v2, 0xfffffc00, v2
	v_sub_u32_e32 v0, v0, v2
	v_lshrrev_b32_e32 v2, 4, v0
	v_bitop3_b32 v2, v2, v0, 32 bitop3:0x6c
	v_ashrrev_i32_e32 v0, 31, v0
	v_lshrrev_b32_e32 v0, 26, v0
	v_add_u32_e32 v0, v2, v0
	v_ashrrev_i32_e32 v14, 6, v0
	v_ashrrev_i32_e32 v0, 31, v18
	v_lshrrev_b32_e32 v0, 26, v0
	v_add_u32_e32 v0, v18, v0
	v_ashrrev_i32_e32 v15, 6, v0
	s_ashr_i32 s3, s13, 6
	v_lshlrev_b32_e32 v0, 3, v15
	s_ashr_i32 s21, s13, 8
	s_lshl_b32 s16, s3, 10
	v_and_b32_e32 v0, -16, v0
	v_add_u32_e32 v3, v14, v0
	v_and_b32_e32 v0, 3, v14
	s_and_b64 s[22:23], s[18:19], exec
	v_and_or_b32 v0, v3, s20, v0
	v_lshrrev_b32_e32 v4, 2, v3
	v_lshlrev_b32_e32 v5, 1, v3
	v_mul_lo_u32 v3, v3, s17
	s_cselect_b32 s17, 25, 24
	s_mul_i32 s17, s12, s17
	s_add_i32 s17, s17, s10
	s_sub_i32 s20, s36, s99
	s_lshr_b32 s20, s20, 3
	s_sub_i32 s17, s17, s20
	s_mul_hi_i32 s20, s17, 0x2aaaaaab
	s_lshr_b32 s22, s20, 31
	s_ashr_i32 s20, s20, 2
	s_add_i32 s20, s20, s22
	s_lshl_b32 s22, s20, 3
	s_mul_i32 s20, s20, 24
	s_sub_i32 s17, s17, s20
	s_bfe_i32 s20, s17, 0x80000
	s_bfe_u32 s20, s20, 0x3000c
	v_and_b32_e32 v4, 4, v4
	v_and_b32_e32 v5, 24, v5
	s_add_i32 s23, s17, s20
	v_or3_b32 v0, v0, v4, v5
	v_lshlrev_b32_e32 v4, 5, v15
	s_bfe_i32 s20, s23, 0x80000
	s_and_b32 s23, s23, 0xf8
	v_and_b32_e32 v16, 32, v4
	v_mul_i32_i24_e32 v4, 64, v14
	s_sext_i32_i16 s20, s20
	s_sub_i32 s17, s17, s23
	v_sub_u32_e32 v2, v2, v4
	s_lshr_b32 s20, s20, 3
	s_sext_i32_i8 s17, s17
	v_ashrrev_i16_sdwa v2, v242, sext(v2) dst_sel:DWORD dst_unused:UNUSED_PAD src0_sel:DWORD src1_sel:BYTE_0
	s_add_i32 s59, s22, s17
	s_bfe_i64 s[22:23], s[20:21], 0x100000
	v_bfe_i32 v17, v2, 0, 16
	s_lshl_b64 s[22:23], s[22:23], 17
	v_readlane_b32 s17, v253, 22
	v_add_u32_e32 v2, v16, v17
	s_add_u32 s26, s17, s22
	v_readlane_b32 s17, v253, 23
	v_lshlrev_b32_e32 v4, 1, v2
	s_addc_u32 s27, s17, s23
	s_add_i32 s17, s16, 0
	v_lshl_add_u32 v0, v0, 9, v4
	s_add_i32 m0, s17, 0x10000
	s_mul_i32 s25, s59, 0x240000
	global_load_lds_dwordx4 v0, s[26:27]
	s_add_i32 m0, s17, 0x12000
	s_add_u32 s22, s26, 0x10000
	global_load_lds_dwordx4 v154, s[26:27]
	s_addc_u32 s23, s27, 0
	s_add_i32 m0, s17, 0x14000
	s_mul_hi_i32 s24, s59, 0x240000
	global_load_lds_dwordx4 v0, s[22:23]
	s_add_i32 m0, s17, 0x16000
	v_add_lshl_u32 v158, v2, v3, 1
	global_load_lds_dwordx4 v154, s[22:23]
	v_readlane_b32 s22, v253, 20
	s_add_u32 s46, s22, s25
	v_readlane_b32 s22, v253, 21
	s_addc_u32 s47, s22, s24
	s_add_i32 s34, s17, 0x2000
	s_mov_b32 m0, s17
	s_add_u32 s22, s46, 0x120000
	global_load_lds_dwordx4 v158, s[46:47]
	s_mov_b32 m0, s34
	s_addc_u32 s23, s47, 0
	s_add_i32 s48, s17, 0x4000
	global_load_lds_dwordx4 v156, s[46:47]
	s_mov_b32 m0, s48
	s_add_i32 s49, s17, 0x6000
	global_load_lds_dwordx4 v158, s[22:23]
	s_mov_b32 m0, s49
	v_mov_b32_e32 v155, v1
	global_load_lds_dwordx4 v156, s[22:23]
	v_mov_b32_e32 v159, v1
	v_mov_b32_e32 v157, v1
	v_lshl_add_u64 v[8:9], s[26:27], 0, v[0:1]
	v_lshl_add_u64 v[6:7], s[26:27], 0, v[154:155]
	v_lshl_add_u64 v[4:5], s[46:47], 0, v[158:159]
	s_cmp_lg_u32 s21, 1
	v_lshl_add_u64 v[2:3], s[46:47], 0, v[156:157]
	s_cbranch_scc1 .LBB0_103
	s_barrier

;     __host__ __device__ bool next(int i, Unit& u) const {
;         const long L = (long)i * G + c; if (L >= nwg) return false;
;         int wgid = (int)L; { const int q = nwg / NXCD, r = nwg % NXCD, xcd = wgid % NXCD, off = wgid / NXCD; wgid = (xcd < r ? xcd * (q + 1) : r * (q + 1) + (xcd - r) * q) + off; }
;         const int nig = WGM * nN, gid = wgid / nig, fm = gid * WGM, gsz = (nM - fm) < WGM ? (nM - fm) : WGM;
;         u.pm = fm + ((wgid % nig) % gsz); u.pn = (wgid % nig) / gsz; return true;
;     }
; template <class Epi, class Sched, bool ALIGN_EPI>
; __device__ __forceinline__ void gemm_phase(PG8_LAS unsigned char* lds, const Gemm g, const Sched& S, const Epi& E) {
;     ...
;     for (;;) {
;         const bool has_next = S.next(ui + 1, nxt);
;         const char* nA = has_next ? (const char*)g.A + (size_t)nxt.pm * tstepA : cA; const char* nB = has_next ? (const char*)g.Bt + (size_t)nxt.pn * tstepB : cB;
.LBB0_105:
	s_add_i32 s61, s61, 1
	s_mul_i32 s2, s61, s31
	s_mul_hi_u32 s3, s61, s98
	s_add_i32 s3, s3, s2
	s_mul_i32 s2, s61, s98
	s_add_u32 s2, s2, s99
	s_addc_u32 s3, s3, s54
	v_mov_b64_e32 v[2:3], 0xc0
	v_cmp_lt_i64_e64 s[42:43], s[2:3], v[2:3]
	v_mov_b64_e32 v[2:3], 0xbf
	v_cmp_gt_i64_e64 s[40:41], s[2:3], v[2:3]
	s_and_b64 vcc, exec, s[40:41]
	s_cbranch_vccnz .LBB0_107
	s_ashr_i32 s3, s2, 31
	s_lshr_b32 s3, s3, 29
	s_add_i32 s3, s2, s3
	s_ashr_i32 s22, s3, 3
	s_and_b32 s3, s3, -8
	s_sub_i32 s2, s2, s3
	s_cmp_lt_i32 s2, 0
	s_cselect_b32 s3, 25, 24
	s_mul_i32 s2, s2, s3
	s_add_i32 s2, s2, s22
	s_mul_hi_i32 s3, s2, 0x2aaaaaab
	s_lshr_b32 s22, s3, 31
	s_ashr_i32 s3, s3, 2
	s_add_i32 s3, s3, s22
	s_lshl_b32 s23, s3, 3
	s_sub_i32 s22, 64, s23
	s_min_i32 s24, s22, 8
	s_abs_i32 s22, s24
	v_cvt_f32_u32_e32 v2, s22
	s_sub_i32 s28, 0, s22
	s_mul_i32 s3, s3, 24
	s_sub_i32 s2, s2, s3
	v_rcp_iflag_f32_e32 v2, v2
	s_abs_i32 s3, s2
	s_xor_b32 s25, s2, s24
	s_ashr_i32 s25, s25, 31
	v_mul_f32_e32 v2, 0x4f7ffffe, v2
	v_cvt_u32_f32_e32 v2, v2
	s_nop 0
	v_readfirstlane_b32 s29, v2
	s_mul_i32 s28, s28, s29
	s_mul_hi_u32 s28, s29, s28
	s_add_i32 s29, s29, s28
	s_mul_hi_u32 s28, s3, s29
	s_mul_i32 s29, s28, s22
	s_sub_i32 s3, s3, s29
	s_add_i32 s44, s28, 1
	s_sub_i32 s29, s3, s22
	s_cmp_ge_u32 s3, s22
	s_cselect_b32 s28, s44, s28
	s_cselect_b32 s3, s29, s3
	s_add_i32 s29, s28, 1
	s_cmp_ge_u32 s3, s22
	s_cselect_b32 s3, s29, s28
	s_xor_b32 s3, s3, s25
	s_sub_i32 s22, s3, s25
	s_mul_i32 s3, s22, s24
	s_sub_i32 s2, s2, s3
	s_add_i32 s89, s23, s2
